# S5 discretisation B-bar steps software-pipelined (loads of the next step issued before the previous store, vmcnt(1))
# baseline (speedup 1.0000x reference)
; DI void cvt_next(const Params& p, char* smem, int nl, int t) {
;     ...
;               float* S5P = (float*)(ws + WS_S5P);
;               int gp = e * 256 + tid;
;               int g = gp >> 6;
;               float dt = expf(p.log_dt[nli * 64 + g]);
;               float lr = p.lam_re[nli * 4096 + gp], lim = p.lam_im[nli * 4096 + gp];
;               float mag = expf(lr * dt);
;               float abr = mag * cosf(lim * dt), abi = mag * sinf(lim * dt);
;               float den = lr * lr + lim * lim;
;               float nr = abr - 1.f;
;               float fre = (nr * lr + abi * lim) / den;
;               float fim = (abi * lr - nr * lim) / den;
;               S5P[gp] = abr;
;               S5P[4096 + gp] = abi;
;               float ar = abr, ai = abi;
; #pragma unroll
;               for (int q = 0; q < 7; ++q) { float nr2 = ar * ar - ai * ai; ai = 2.f * ar * ai; ar = nr2; }
;               S5P[8192 + gp] = ar;
;               S5P[12288 + gp] = ai;
;               const float* br = p.b_re + (size_t)nli * 65536 + gp * 16;
;               const float* bi = p.b_im + (size_t)nli * 65536 + gp * 16;
; #pragma unroll
;               for (int c = 0; c < 16; ++c) {
;                 S5P[16384 + gp * 16 + c] = fre * br[c] - fim * bi[c];
;                 S5P[16384 + 65536 + gp * 16 + c] = fre * bi[c] + fim * br[c];
.LBB0_982:
	s_or_b64 exec, exec, s[0:1]
	s_waitcnt vmcnt(0)
	v_mul_f32_e32 v7, v7, v4
	v_mul_f32_e32 v10, 0x3fb8aa3b, v7
	v_fma_f32 v11, v7, s66, -v10
	v_rndne_f32_e32 v13, v10
	v_fmac_f32_e32 v11, 0x32a5705f, v7
	v_sub_f32_e32 v10, v10, v13
	v_add_f32_e32 v10, v10, v11
	v_exp_f32_e32 v10, v10
	v_cvt_i32_f32_e32 v11, v13
	s_mov_b32 s0, 0xc2ce8ed0
	v_cmp_ngt_f32_e32 vcc, s0, v7
	s_mov_b32 s0, 0x42b17218
	v_ldexp_f32 v10, v10, v11
	v_cndmask_b32_e32 v10, 0, v10, vcc
	v_cmp_nlt_f32_e32 vcc, s0, v7
	s_brev_b32 s0, 1
	s_nop 0
	v_cndmask_b32_e32 v7, v224, v10, vcc
	v_mul_f32_e32 v10, v9, v9
	v_fmamk_f32 v11, v10, 0xb94c1982, v217
	v_fmaak_f32 v11, v10, v11, 0xbe2aaa9d
	v_mul_f32_e32 v11, v10, v11
	v_fmac_f32_e32 v9, v9, v11
	v_fmamk_f32 v11, v10, 0x37d75334, v218
	v_fmaak_f32 v11, v10, v11, 0x3d2aabf7
	v_fmaak_f32 v11, v10, v11, 0xbf000004
	v_fma_f32 v10, v10, v11, 1.0
	v_and_b32_e32 v11, 1, v8
	v_cmp_eq_u32_e32 vcc, 0, v11
	v_lshlrev_b32_e32 v8, 30, v8
	s_nop 0
	v_cndmask_b32_e64 v9, -v9, v10, vcc
	v_bitop3_b32 v8, v8, v9, s0 bitop3:0x6c
	v_mul_f32_e32 v9, v12, v12
	v_fmamk_f32 v11, v9, 0xb94c1982, v217
	v_fmaak_f32 v11, v9, v11, 0xbe2aaa9d
	v_mul_f32_e32 v11, v9, v11
	v_fmac_f32_e32 v12, v12, v11
	v_fmamk_f32 v11, v9, 0x37d75334, v218
	v_fmaak_f32 v11, v9, v11, 0x3d2aabf7
	v_fmaak_f32 v11, v9, v11, 0xbf000004
	s_movk_i32 s0, 0x1f8
	v_fma_f32 v9, v9, v11, 1.0
	v_and_b32_e32 v11, 1, v0
	v_lshlrev_b32_e32 v0, 30, v0
	v_cmp_class_f32_e64 vcc, v5, s0
	v_cmp_eq_u32_e64 s[12:13], 0, v11
	v_and_b32_e32 v0, 0x80000000, v0
	v_xor_b32_e32 v5, v6, v5
	v_cndmask_b32_e64 v9, v9, v12, s[12:13]
	v_xor_b32_e32 v0, v5, v0
	v_xor_b32_e32 v0, v0, v9
	v_cndmask_b32_e32 v8, v227, v8, vcc
	v_cndmask_b32_e32 v0, v227, v0, vcc
	v_mul_f32_e32 v0, v7, v0
	v_fma_f32 v6, v7, v8, -1.0
	v_mul_f32_e32 v5, v3, v3
	v_mul_f32_e32 v11, v3, v0
	v_mul_f32_e32 v3, v3, v6
	v_readlane_b32 s0, v255, 30
	v_fma_f32 v12, v4, v0, -v3
	v_ashrrev_i32_e32 v3, 31, v2
	v_readlane_b32 s1, v255, 31
	v_mul_f32_e32 v10, v7, v8
	v_fmac_f32_e32 v11, v4, v6
	v_lshl_add_u64 v[8:9], v[2:3], 2, s[0:1]
	s_movk_i32 s0, 0x4000
	v_add_co_u32_e32 v6, vcc, s0, v8
	v_mul_f32_e32 v3, v0, v0
	s_nop 0
	v_addc_co_u32_e32 v7, vcc, 0, v9, vcc
	global_store_dword v[6:7], v0, off
	v_add_f32_e32 v6, v10, v10
	v_mul_f32_e32 v0, v6, v0
	v_fma_f32 v3, v10, v10, -v3
	v_mul_f32_e32 v6, v0, v0
	v_fma_f32 v6, v3, v3, -v6
	v_add_f32_e32 v3, v3, v3
	v_mul_f32_e32 v0, v0, v3
	v_mul_f32_e32 v3, v0, v0
	v_fma_f32 v3, v6, v6, -v3
	v_add_f32_e32 v6, v6, v6
	v_mul_f32_e32 v0, v0, v6
	v_mul_f32_e32 v6, v0, v0
	v_fma_f32 v6, v3, v3, -v6
	v_add_f32_e32 v3, v3, v3
	v_mul_f32_e32 v0, v0, v3
	v_mul_f32_e32 v3, v0, v0
	v_fma_f32 v3, v6, v6, -v3
	v_add_f32_e32 v6, v6, v6
	v_mul_f32_e32 v0, v0, v6
	v_mul_f32_e32 v6, v0, v0
	v_fma_f32 v6, v3, v3, -v6
	v_add_f32_e32 v3, v3, v3
	v_mul_f32_e32 v0, v0, v3
	v_mul_f32_e32 v3, v0, v0
	v_fma_f32 v3, v6, v6, -v3
	v_add_f32_e32 v6, v6, v6
	v_fmac_f32_e32 v5, v4, v4
	v_mul_f32_e32 v6, v0, v6
	v_div_scale_f32 v0, s[0:1], v5, v5, v11
	v_rcp_f32_e32 v4, v0
	global_store_dword v[8:9], v10, off
	v_fma_f32 v7, -v0, v4, 1.0
	v_fmac_f32_e32 v4, v7, v4
	v_div_scale_f32 v7, vcc, v11, v5, v11
	v_mul_f32_e32 v10, v7, v4
	v_fma_f32 v13, -v0, v10, v7
	v_fmac_f32_e32 v10, v13, v4
	v_fma_f32 v0, -v0, v10, v7
	v_div_fmas_f32 v0, v0, v4, v10
	v_div_scale_f32 v4, s[0:1], v5, v5, v12
	v_rcp_f32_e32 v7, v4
	v_div_fixup_f32 v0, v0, v5, v11
	s_mov_b32 s0, 0x8000
	v_fma_f32 v10, -v4, v7, 1.0
	v_fmac_f32_e32 v7, v10, v7
	v_div_scale_f32 v10, vcc, v12, v5, v12
	v_mul_f32_e32 v11, v10, v7
	v_fma_f32 v13, -v4, v11, v10
	v_fmac_f32_e32 v11, v13, v7
	v_fma_f32 v4, -v4, v11, v10
	v_div_fmas_f32 v4, v4, v7, v11
	v_div_fixup_f32 v10, v4, v5, v12
	v_add_co_u32_e32 v4, vcc, s0, v8
	s_mov_b32 s0, 0xc000
	s_nop 0
	v_addc_co_u32_e32 v5, vcc, 0, v9, vcc
	global_store_dword v[4:5], v3, off
	v_add_co_u32_e32 v4, vcc, s0, v8
	v_readlane_b32 s0, v255, 4
	v_readlane_b32 s1, v255, 5
	s_load_dwordx4 s[12:15], s[0:1], 0x68
	v_addc_co_u32_e32 v5, vcc, 0, v9, vcc
	global_store_dword v[4:5], v6, off
	v_lshlrev_b32_e32 v4, 4, v2
	s_waitcnt lgkmcnt(0)
	s_add_u32 s0, s12, s44
	v_ashrrev_i32_e32 v5, 31, v4
	s_addc_u32 s1, s13, s45
	v_lshlrev_b64 v[6:7], 2, v[4:5]
	v_lshl_add_u64 v[4:5], s[0:1], 0, v[6:7]
	s_add_u32 s0, s14, s44
	s_addc_u32 s1, s15, s45
	v_lshl_add_u64 v[6:7], s[0:1], 0, v[6:7]
	global_load_dword v3, v[4:5], off
	global_load_dword v11, v[6:7], off
	v_mad_i64_i32 v[8:9], s[0:1], v2, 60, v[8:9]
	s_mov_b32 s0, 0x10000
	s_nop 0
	v_add_co_u32_e32 v2, vcc, s0, v8
	s_mov_b32 s0, 0x50000
	s_waitcnt vmcnt(0)
	v_mul_f32_e32 v11, v11, v10
	v_fma_f32 v11, v3, v0, -v11
	v_addc_co_u32_e32 v3, vcc, 0, v9, vcc
	global_store_dword v[2:3], v11, off
	global_load_dword v11, v[6:7], off
	s_nop 0
	global_load_dword v12, v[4:5], off
	v_add_co_u32_e32 v8, vcc, s0, v8
	s_mov_b64 s[0:1], 0
	s_nop 0
	v_addc_co_u32_e32 v9, vcc, 0, v9, vcc
	s_waitcnt vmcnt(0)
	v_mul_f32_e32 v12, v12, v10
	v_fmac_f32_e32 v12, v11, v0
	global_store_dword v[8:9], v12, off
	global_load_dword v11, v[4:5], off offset:4
	s_nop 0
	global_load_dword v12, v[6:7], off offset:4
	s_waitcnt vmcnt(0)
	v_mul_f32_e32 v12, v10, v12
	v_fma_f32 v11, v0, v11, -v12
	global_load_dword v26, v[6:7], off offset:4
	s_nop 0
	global_load_dword v27, v[4:5], off offset:4
	global_store_dword v[2:3], v11, off offset:4
	s_waitcnt vmcnt(1)
	v_mul_f32_e32 v27, v10, v27
	v_fmac_f32_e32 v27, v0, v26
	global_load_dword v11, v[4:5], off offset:8
	s_nop 0
	global_load_dword v12, v[6:7], off offset:8
	global_store_dword v[8:9], v27, off offset:4
	s_waitcnt vmcnt(1)
; DI void cvt_next(const Params& p, char* smem, int nl, int t) {
;     ...
;               for (int c = 0; c < 16; ++c) {
;                 S5P[16384 + gp * 16 + c] = fre * br[c] - fim * bi[c];
;                 S5P[16384 + 65536 + gp * 16 + c] = fre * bi[c] + fim * br[c];
	v_mul_f32_e32 v12, v10, v12
	v_fma_f32 v11, v0, v11, -v12
	global_load_dword v26, v[6:7], off offset:8
	s_nop 0
	global_load_dword v27, v[4:5], off offset:8
	global_store_dword v[2:3], v11, off offset:8
	s_waitcnt vmcnt(1)
	v_mul_f32_e32 v27, v10, v27
	v_fmac_f32_e32 v27, v0, v26
	global_load_dword v11, v[4:5], off offset:12
	s_nop 0
	global_load_dword v12, v[6:7], off offset:12
	global_store_dword v[8:9], v27, off offset:8
	s_waitcnt vmcnt(1)
	v_mul_f32_e32 v12, v10, v12
	v_fma_f32 v11, v0, v11, -v12
	global_load_dword v26, v[6:7], off offset:12
	s_nop 0
	global_load_dword v27, v[4:5], off offset:12
	global_store_dword v[2:3], v11, off offset:12
	s_waitcnt vmcnt(1)
	v_mul_f32_e32 v27, v10, v27
	v_fmac_f32_e32 v27, v0, v26
	global_load_dword v11, v[4:5], off offset:16
	s_nop 0
	global_load_dword v12, v[6:7], off offset:16
	global_store_dword v[8:9], v27, off offset:12
	s_waitcnt vmcnt(1)
	v_mul_f32_e32 v12, v10, v12
	v_fma_f32 v11, v0, v11, -v12
	global_load_dword v26, v[6:7], off offset:16
	s_nop 0
	global_load_dword v27, v[4:5], off offset:16
	global_store_dword v[2:3], v11, off offset:16
	s_waitcnt vmcnt(1)
	v_mul_f32_e32 v27, v10, v27
	v_fmac_f32_e32 v27, v0, v26
	global_load_dword v11, v[4:5], off offset:20
	s_nop 0
	global_load_dword v12, v[6:7], off offset:20
	global_store_dword v[8:9], v27, off offset:16
	s_waitcnt vmcnt(1)
	v_mul_f32_e32 v12, v10, v12
	v_fma_f32 v11, v0, v11, -v12
	global_load_dword v26, v[6:7], off offset:20
	s_nop 0
	global_load_dword v27, v[4:5], off offset:20
	global_store_dword v[2:3], v11, off offset:20
	s_waitcnt vmcnt(1)
	v_mul_f32_e32 v27, v10, v27
	v_fmac_f32_e32 v27, v0, v26
	global_load_dword v11, v[4:5], off offset:24
	s_nop 0
	global_load_dword v12, v[6:7], off offset:24
	global_store_dword v[8:9], v27, off offset:20
	s_waitcnt vmcnt(1)
	v_mul_f32_e32 v12, v10, v12
	v_fma_f32 v11, v0, v11, -v12
	global_load_dword v26, v[6:7], off offset:24
	s_nop 0
	global_load_dword v27, v[4:5], off offset:24
	global_store_dword v[2:3], v11, off offset:24
	s_waitcnt vmcnt(1)
	v_mul_f32_e32 v27, v10, v27
	v_fmac_f32_e32 v27, v0, v26
	global_load_dword v11, v[4:5], off offset:28
	s_nop 0
	global_load_dword v12, v[6:7], off offset:28
	global_store_dword v[8:9], v27, off offset:24
	s_waitcnt vmcnt(1)
	v_mul_f32_e32 v12, v10, v12
	v_fma_f32 v11, v0, v11, -v12
	global_load_dword v26, v[6:7], off offset:28
	s_nop 0
	global_load_dword v27, v[4:5], off offset:28
	global_store_dword v[2:3], v11, off offset:28
	s_waitcnt vmcnt(1)
	v_mul_f32_e32 v27, v10, v27
	v_fmac_f32_e32 v27, v0, v26
	global_load_dword v11, v[4:5], off offset:32
	s_nop 0
	global_load_dword v12, v[6:7], off offset:32
	global_store_dword v[8:9], v27, off offset:28
	s_waitcnt vmcnt(1)
	v_mul_f32_e32 v12, v10, v12
	v_fma_f32 v11, v0, v11, -v12
	global_load_dword v26, v[6:7], off offset:32
	s_nop 0
	global_load_dword v27, v[4:5], off offset:32
	global_store_dword v[2:3], v11, off offset:32
	s_waitcnt vmcnt(1)
	v_mul_f32_e32 v27, v10, v27
	v_fmac_f32_e32 v27, v0, v26
	global_load_dword v11, v[4:5], off offset:36
	s_nop 0
	global_load_dword v12, v[6:7], off offset:36
	global_store_dword v[8:9], v27, off offset:32
	s_waitcnt vmcnt(1)
	v_mul_f32_e32 v12, v10, v12
	v_fma_f32 v11, v0, v11, -v12
	global_load_dword v26, v[6:7], off offset:36
	s_nop 0
	global_load_dword v27, v[4:5], off offset:36
	global_store_dword v[2:3], v11, off offset:36
	s_waitcnt vmcnt(1)
	v_mul_f32_e32 v27, v10, v27
	v_fmac_f32_e32 v27, v0, v26
	global_load_dword v11, v[4:5], off offset:40
	s_nop 0
	global_load_dword v12, v[6:7], off offset:40
	global_store_dword v[8:9], v27, off offset:36
	s_waitcnt vmcnt(1)
	v_mul_f32_e32 v12, v10, v12
	v_fma_f32 v11, v0, v11, -v12
	global_load_dword v26, v[6:7], off offset:40
	s_nop 0
	global_load_dword v27, v[4:5], off offset:40
	global_store_dword v[2:3], v11, off offset:40
	s_waitcnt vmcnt(1)
	v_mul_f32_e32 v27, v10, v27
	v_fmac_f32_e32 v27, v0, v26
	global_load_dword v11, v[4:5], off offset:44
	s_nop 0
	global_load_dword v12, v[6:7], off offset:44
	global_store_dword v[8:9], v27, off offset:40
	s_waitcnt vmcnt(1)
	v_mul_f32_e32 v12, v10, v12
	v_fma_f32 v11, v0, v11, -v12
	global_load_dword v26, v[6:7], off offset:44
	s_nop 0
	global_load_dword v27, v[4:5], off offset:44
	global_store_dword v[2:3], v11, off offset:44
	s_waitcnt vmcnt(1)
	v_mul_f32_e32 v27, v10, v27
	v_fmac_f32_e32 v27, v0, v26
	global_load_dword v11, v[4:5], off offset:48
	s_nop 0
	global_load_dword v12, v[6:7], off offset:48
	global_store_dword v[8:9], v27, off offset:44
	s_waitcnt vmcnt(1)
	v_mul_f32_e32 v12, v10, v12
	v_fma_f32 v11, v0, v11, -v12
	global_load_dword v26, v[6:7], off offset:48
	s_nop 0
	global_load_dword v27, v[4:5], off offset:48
	global_store_dword v[2:3], v11, off offset:48
	s_waitcnt vmcnt(1)
	v_mul_f32_e32 v27, v10, v27
	v_fmac_f32_e32 v27, v0, v26
	global_load_dword v11, v[4:5], off offset:52
	s_nop 0
	global_load_dword v12, v[6:7], off offset:52
	global_store_dword v[8:9], v27, off offset:48
	s_waitcnt vmcnt(1)
	v_mul_f32_e32 v12, v10, v12
	v_fma_f32 v11, v0, v11, -v12
	global_load_dword v26, v[6:7], off offset:52
	s_nop 0
	global_load_dword v27, v[4:5], off offset:52
	global_store_dword v[2:3], v11, off offset:52
	s_waitcnt vmcnt(1)
	v_mul_f32_e32 v27, v10, v27
	v_fmac_f32_e32 v27, v0, v26
	global_load_dword v11, v[4:5], off offset:56
	s_nop 0
	global_load_dword v12, v[6:7], off offset:56
	global_store_dword v[8:9], v27, off offset:52
	s_waitcnt vmcnt(1)
	v_mul_f32_e32 v12, v10, v12
	v_fma_f32 v11, v0, v11, -v12
	global_load_dword v26, v[6:7], off offset:56
	s_nop 0
	global_load_dword v27, v[4:5], off offset:56
	global_store_dword v[2:3], v11, off offset:56
	s_waitcnt vmcnt(1)
	v_mul_f32_e32 v27, v10, v27
	v_fmac_f32_e32 v27, v0, v26
	global_load_dword v11, v[4:5], off offset:60
	s_nop 0
	global_load_dword v12, v[6:7], off offset:60
	global_store_dword v[8:9], v27, off offset:56
	s_waitcnt vmcnt(1)
	v_mul_f32_e32 v12, v10, v12
	v_fma_f32 v11, v0, v11, -v12
	global_store_dword v[2:3], v11, off offset:60
	global_load_dword v2, v[6:7], off offset:60
	s_nop 0
	global_load_dword v3, v[4:5], off offset:60
	s_waitcnt vmcnt(0)
	v_mul_f32_e32 v3, v10, v3
	v_fmac_f32_e32 v3, v0, v2
	global_store_dword v[8:9], v3, off offset:60
